# phase_mod silu(c) staging: 16 per-thread loads issued together with counted waits (was load-wait-compute per element), on top of v22
# speedup vs baseline: 1.0284x; 1.0000x over previous
; __device__ __forceinline__ void phase_mod(PP p, float* mod, LAS unsigned char* lds, int tid, int lane, int wave) {
;     ...
;     if ((int)blockIdx.x < 192) {
;         for (int i = tid; i < NBATCH * DM; i += 512) { const float v = p->c[i]; sc[i] = v / (1.f + __expf(-v)); }
.LBB0_12:
	s_mov_b64 s[2:3], s[68:69]
	s_mov_b32 s1, s80
	s_mov_b32 s0, 0
	s_waitcnt lgkmcnt(0)
	s_mov_b32 s4, 0
	s_cmpk_gt_i32 s73, 0xbf
	s_barrier
	s_cbranch_scc1 .LBB0_25
	v_mbcnt_lo_u32_b32 v2, -1, s4
	v_mbcnt_hi_u32_b32 v126, -1, v2
	v_lshl_add_u32 v2, s1, 6, v126
	s_movk_i32 s4, 0x1fff
	v_cmp_lt_i32_e32 vcc, s4, v2
	s_and_saveexec_b64 s[4:5], vcc
	s_xor_b64 s[4:5], exec, s[4:5]
	s_lshl_b32 s8, s1, 8
	s_or_saveexec_b64 s[6:7], s[4:5]
	s_load_dwordx2 s[4:5], s[2:3], 0x88
	v_mov_b32_e32 v3, s8
	s_xor_b64 exec, exec, s[6:7]
	s_cbranch_execz .LBB0_19
	s_load_dwordx2 s[8:9], s[2:3], 0x8
	s_lshl_b32 s12, s1, 8
	s_add_i32 s10, s12, 0
	v_ashrrev_i32_e32 v3, 31, v2
	v_add_u32_e32 v4, 0xfffffe00, v2
	v_lshl_add_u32 v5, v126, 2, s10
	s_waitcnt lgkmcnt(0)
	v_lshl_add_u64 v[2:3], v[2:3], 2, s[8:9]
	s_mov_b64 s[8:9], 0
	s_mov_b64 s[10:11], 0x800
	s_movk_i32 s13, 0x1dff
	global_load_dword v190, v[2:3], off
	v_lshl_add_u64 v[2:3], v[2:3], 0, s[10:11]
	global_load_dword v191, v[2:3], off
	v_lshl_add_u64 v[2:3], v[2:3], 0, s[10:11]
	global_load_dword v192, v[2:3], off
	v_lshl_add_u64 v[2:3], v[2:3], 0, s[10:11]
	global_load_dword v193, v[2:3], off
	v_lshl_add_u64 v[2:3], v[2:3], 0, s[10:11]
	global_load_dword v194, v[2:3], off
	v_lshl_add_u64 v[2:3], v[2:3], 0, s[10:11]
	global_load_dword v195, v[2:3], off
	v_lshl_add_u64 v[2:3], v[2:3], 0, s[10:11]
	global_load_dword v196, v[2:3], off
	v_lshl_add_u64 v[2:3], v[2:3], 0, s[10:11]
	global_load_dword v197, v[2:3], off
	v_lshl_add_u64 v[2:3], v[2:3], 0, s[10:11]
	global_load_dword v198, v[2:3], off
	v_lshl_add_u64 v[2:3], v[2:3], 0, s[10:11]
	global_load_dword v199, v[2:3], off
	v_lshl_add_u64 v[2:3], v[2:3], 0, s[10:11]
	global_load_dword v200, v[2:3], off
	v_lshl_add_u64 v[2:3], v[2:3], 0, s[10:11]
	global_load_dword v201, v[2:3], off
	v_lshl_add_u64 v[2:3], v[2:3], 0, s[10:11]
	global_load_dword v202, v[2:3], off
	v_lshl_add_u64 v[2:3], v[2:3], 0, s[10:11]
	global_load_dword v203, v[2:3], off
	v_lshl_add_u64 v[2:3], v[2:3], 0, s[10:11]
	global_load_dword v204, v[2:3], off
	v_lshl_add_u64 v[2:3], v[2:3], 0, s[10:11]
	global_load_dword v205, v[2:3], off
	s_waitcnt vmcnt(15)
	v_mov_b32_e32 v6, v190
	v_mul_f32_e32 v7, 0xbfb8aa3b, v6
	v_exp_f32_e32 v7, v7
	s_nop 0
	v_add_f32_e32 v7, 1.0, v7
	v_div_scale_f32 v8, s[14:15], v7, v7, v6
	v_rcp_f32_e32 v9, v8
	v_div_scale_f32 v10, vcc, v6, v7, v6
	v_fma_f32 v11, -v8, v9, 1.0
	v_fmac_f32_e32 v9, v11, v9
	v_mul_f32_e32 v11, v10, v9
	v_fma_f32 v12, -v8, v11, v10
	v_fmac_f32_e32 v11, v12, v9
	v_fma_f32 v8, -v8, v11, v10
	v_div_fmas_f32 v8, v8, v9, v11
	v_div_fixup_f32 v6, v8, v7, v6
	ds_write_b32 v5, v6
	s_waitcnt vmcnt(14)
	v_mov_b32_e32 v6, v191
	v_mul_f32_e32 v7, 0xbfb8aa3b, v6
	v_exp_f32_e32 v7, v7
	s_nop 0
	v_add_f32_e32 v7, 1.0, v7
	v_div_scale_f32 v8, s[14:15], v7, v7, v6
	v_rcp_f32_e32 v9, v8
	v_div_scale_f32 v10, vcc, v6, v7, v6
	v_fma_f32 v11, -v8, v9, 1.0
	v_fmac_f32_e32 v9, v11, v9
	v_mul_f32_e32 v11, v10, v9
	v_fma_f32 v12, -v8, v11, v10
	v_fmac_f32_e32 v11, v12, v9
	v_fma_f32 v8, -v8, v11, v10
	v_div_fmas_f32 v8, v8, v9, v11
	v_div_fixup_f32 v6, v8, v7, v6
	ds_write_b32 v5, v6 offset:2048
	s_waitcnt vmcnt(13)
	v_mov_b32_e32 v6, v192
	v_mul_f32_e32 v7, 0xbfb8aa3b, v6
	v_exp_f32_e32 v7, v7
	s_nop 0
	v_add_f32_e32 v7, 1.0, v7
	v_div_scale_f32 v8, s[14:15], v7, v7, v6
	v_rcp_f32_e32 v9, v8
	v_div_scale_f32 v10, vcc, v6, v7, v6
	v_fma_f32 v11, -v8, v9, 1.0
	v_fmac_f32_e32 v9, v11, v9
	v_mul_f32_e32 v11, v10, v9
	v_fma_f32 v12, -v8, v11, v10
	v_fmac_f32_e32 v11, v12, v9
	v_fma_f32 v8, -v8, v11, v10
	v_div_fmas_f32 v8, v8, v9, v11
	v_div_fixup_f32 v6, v8, v7, v6
	ds_write_b32 v5, v6 offset:4096
	s_waitcnt vmcnt(12)
	v_mov_b32_e32 v6, v193
	v_mul_f32_e32 v7, 0xbfb8aa3b, v6
	v_exp_f32_e32 v7, v7
	s_nop 0
	v_add_f32_e32 v7, 1.0, v7
	v_div_scale_f32 v8, s[14:15], v7, v7, v6
	v_rcp_f32_e32 v9, v8
	v_div_scale_f32 v10, vcc, v6, v7, v6
	v_fma_f32 v11, -v8, v9, 1.0
	v_fmac_f32_e32 v9, v11, v9
	v_mul_f32_e32 v11, v10, v9
	v_fma_f32 v12, -v8, v11, v10
	v_fmac_f32_e32 v11, v12, v9
	v_fma_f32 v8, -v8, v11, v10
	v_div_fmas_f32 v8, v8, v9, v11
	v_div_fixup_f32 v6, v8, v7, v6
	ds_write_b32 v5, v6 offset:6144
	s_waitcnt vmcnt(11)
	v_mov_b32_e32 v6, v194
	v_mul_f32_e32 v7, 0xbfb8aa3b, v6
	v_exp_f32_e32 v7, v7
	s_nop 0
	v_add_f32_e32 v7, 1.0, v7
	v_div_scale_f32 v8, s[14:15], v7, v7, v6
	v_rcp_f32_e32 v9, v8
	v_div_scale_f32 v10, vcc, v6, v7, v6
	v_fma_f32 v11, -v8, v9, 1.0
	v_fmac_f32_e32 v9, v11, v9
	v_mul_f32_e32 v11, v10, v9
	v_fma_f32 v12, -v8, v11, v10
	v_fmac_f32_e32 v11, v12, v9
	v_fma_f32 v8, -v8, v11, v10
	v_div_fmas_f32 v8, v8, v9, v11
	v_div_fixup_f32 v6, v8, v7, v6
	ds_write_b32 v5, v6 offset:8192
	s_waitcnt vmcnt(10)
	v_mov_b32_e32 v6, v195
	v_mul_f32_e32 v7, 0xbfb8aa3b, v6
	v_exp_f32_e32 v7, v7
	s_nop 0
	v_add_f32_e32 v7, 1.0, v7
	v_div_scale_f32 v8, s[14:15], v7, v7, v6
	v_rcp_f32_e32 v9, v8
	v_div_scale_f32 v10, vcc, v6, v7, v6
	v_fma_f32 v11, -v8, v9, 1.0
	v_fmac_f32_e32 v9, v11, v9
	v_mul_f32_e32 v11, v10, v9
	v_fma_f32 v12, -v8, v11, v10
	v_fmac_f32_e32 v11, v12, v9
	v_fma_f32 v8, -v8, v11, v10
	v_div_fmas_f32 v8, v8, v9, v11
	v_div_fixup_f32 v6, v8, v7, v6
	ds_write_b32 v5, v6 offset:10240
	s_waitcnt vmcnt(9)
; __device__ __forceinline__ void phase_mod(PP p, float* mod, LAS unsigned char* lds, int tid, int lane, int wave) {
;     ...
;         for (int i = tid; i < NBATCH * DM; i += 512) { const float v = p->c[i]; sc[i] = v / (1.f + __expf(-v)); }
	v_mov_b32_e32 v6, v196
	v_mul_f32_e32 v7, 0xbfb8aa3b, v6
	v_exp_f32_e32 v7, v7
	s_nop 0
	v_add_f32_e32 v7, 1.0, v7
	v_div_scale_f32 v8, s[14:15], v7, v7, v6
	v_rcp_f32_e32 v9, v8
	v_div_scale_f32 v10, vcc, v6, v7, v6
	v_fma_f32 v11, -v8, v9, 1.0
	v_fmac_f32_e32 v9, v11, v9
	v_mul_f32_e32 v11, v10, v9
	v_fma_f32 v12, -v8, v11, v10
	v_fmac_f32_e32 v11, v12, v9
	v_fma_f32 v8, -v8, v11, v10
	v_div_fmas_f32 v8, v8, v9, v11
	v_div_fixup_f32 v6, v8, v7, v6
	ds_write_b32 v5, v6 offset:12288
	s_waitcnt vmcnt(8)
	v_mov_b32_e32 v6, v197
	v_mul_f32_e32 v7, 0xbfb8aa3b, v6
	v_exp_f32_e32 v7, v7
	s_nop 0
	v_add_f32_e32 v7, 1.0, v7
	v_div_scale_f32 v8, s[14:15], v7, v7, v6
	v_rcp_f32_e32 v9, v8
	v_div_scale_f32 v10, vcc, v6, v7, v6
	v_fma_f32 v11, -v8, v9, 1.0
	v_fmac_f32_e32 v9, v11, v9
	v_mul_f32_e32 v11, v10, v9
	v_fma_f32 v12, -v8, v11, v10
	v_fmac_f32_e32 v11, v12, v9
	v_fma_f32 v8, -v8, v11, v10
	v_div_fmas_f32 v8, v8, v9, v11
	v_div_fixup_f32 v6, v8, v7, v6
	ds_write_b32 v5, v6 offset:14336
	s_waitcnt vmcnt(7)
	v_mov_b32_e32 v6, v198
	v_mul_f32_e32 v7, 0xbfb8aa3b, v6
	v_exp_f32_e32 v7, v7
	s_nop 0
	v_add_f32_e32 v7, 1.0, v7
	v_div_scale_f32 v8, s[14:15], v7, v7, v6
	v_rcp_f32_e32 v9, v8
	v_div_scale_f32 v10, vcc, v6, v7, v6
	v_fma_f32 v11, -v8, v9, 1.0
	v_fmac_f32_e32 v9, v11, v9
	v_mul_f32_e32 v11, v10, v9
	v_fma_f32 v12, -v8, v11, v10
	v_fmac_f32_e32 v11, v12, v9
	v_fma_f32 v8, -v8, v11, v10
	v_div_fmas_f32 v8, v8, v9, v11
	v_div_fixup_f32 v6, v8, v7, v6
	ds_write_b32 v5, v6 offset:16384
	s_waitcnt vmcnt(6)
	v_mov_b32_e32 v6, v199
	v_mul_f32_e32 v7, 0xbfb8aa3b, v6
	v_exp_f32_e32 v7, v7
	s_nop 0
	v_add_f32_e32 v7, 1.0, v7
	v_div_scale_f32 v8, s[14:15], v7, v7, v6
	v_rcp_f32_e32 v9, v8
	v_div_scale_f32 v10, vcc, v6, v7, v6
	v_fma_f32 v11, -v8, v9, 1.0
	v_fmac_f32_e32 v9, v11, v9
	v_mul_f32_e32 v11, v10, v9
	v_fma_f32 v12, -v8, v11, v10
	v_fmac_f32_e32 v11, v12, v9
	v_fma_f32 v8, -v8, v11, v10
	v_div_fmas_f32 v8, v8, v9, v11
	v_div_fixup_f32 v6, v8, v7, v6
	ds_write_b32 v5, v6 offset:18432
	s_waitcnt vmcnt(5)
	v_mov_b32_e32 v6, v200
	v_mul_f32_e32 v7, 0xbfb8aa3b, v6
	v_exp_f32_e32 v7, v7
	s_nop 0
	v_add_f32_e32 v7, 1.0, v7
	v_div_scale_f32 v8, s[14:15], v7, v7, v6
	v_rcp_f32_e32 v9, v8
	v_div_scale_f32 v10, vcc, v6, v7, v6
	v_fma_f32 v11, -v8, v9, 1.0
	v_fmac_f32_e32 v9, v11, v9
	v_mul_f32_e32 v11, v10, v9
	v_fma_f32 v12, -v8, v11, v10
	v_fmac_f32_e32 v11, v12, v9
	v_fma_f32 v8, -v8, v11, v10
	v_div_fmas_f32 v8, v8, v9, v11
	v_div_fixup_f32 v6, v8, v7, v6
	ds_write_b32 v5, v6 offset:20480
	s_waitcnt vmcnt(4)
	v_mov_b32_e32 v6, v201
	v_mul_f32_e32 v7, 0xbfb8aa3b, v6
	v_exp_f32_e32 v7, v7
	s_nop 0
	v_add_f32_e32 v7, 1.0, v7
	v_div_scale_f32 v8, s[14:15], v7, v7, v6
	v_rcp_f32_e32 v9, v8
	v_div_scale_f32 v10, vcc, v6, v7, v6
	v_fma_f32 v11, -v8, v9, 1.0
	v_fmac_f32_e32 v9, v11, v9
	v_mul_f32_e32 v11, v10, v9
	v_fma_f32 v12, -v8, v11, v10
	v_fmac_f32_e32 v11, v12, v9
	v_fma_f32 v8, -v8, v11, v10
	v_div_fmas_f32 v8, v8, v9, v11
	v_div_fixup_f32 v6, v8, v7, v6
	ds_write_b32 v5, v6 offset:22528
	s_waitcnt vmcnt(3)
	v_mov_b32_e32 v6, v202
	v_mul_f32_e32 v7, 0xbfb8aa3b, v6
	v_exp_f32_e32 v7, v7
	s_nop 0
	v_add_f32_e32 v7, 1.0, v7
	v_div_scale_f32 v8, s[14:15], v7, v7, v6
	v_rcp_f32_e32 v9, v8
	v_div_scale_f32 v10, vcc, v6, v7, v6
	v_fma_f32 v11, -v8, v9, 1.0
	v_fmac_f32_e32 v9, v11, v9
	v_mul_f32_e32 v11, v10, v9
	v_fma_f32 v12, -v8, v11, v10
	v_fmac_f32_e32 v11, v12, v9
	v_fma_f32 v8, -v8, v11, v10
	v_div_fmas_f32 v8, v8, v9, v11
	v_div_fixup_f32 v6, v8, v7, v6
	ds_write_b32 v5, v6 offset:24576
	s_waitcnt vmcnt(2)
	v_mov_b32_e32 v6, v203
	v_mul_f32_e32 v7, 0xbfb8aa3b, v6
	v_exp_f32_e32 v7, v7
	s_nop 0
	v_add_f32_e32 v7, 1.0, v7
	v_div_scale_f32 v8, s[14:15], v7, v7, v6
	v_rcp_f32_e32 v9, v8
	v_div_scale_f32 v10, vcc, v6, v7, v6
	v_fma_f32 v11, -v8, v9, 1.0
	v_fmac_f32_e32 v9, v11, v9
	v_mul_f32_e32 v11, v10, v9
	v_fma_f32 v12, -v8, v11, v10
	v_fmac_f32_e32 v11, v12, v9
	v_fma_f32 v8, -v8, v11, v10
	v_div_fmas_f32 v8, v8, v9, v11
	v_div_fixup_f32 v6, v8, v7, v6
	ds_write_b32 v5, v6 offset:26624
	s_waitcnt vmcnt(1)
	v_mov_b32_e32 v6, v204
	v_mul_f32_e32 v7, 0xbfb8aa3b, v6
	v_exp_f32_e32 v7, v7
	s_nop 0
	v_add_f32_e32 v7, 1.0, v7
	v_div_scale_f32 v8, s[14:15], v7, v7, v6
	v_rcp_f32_e32 v9, v8
	v_div_scale_f32 v10, vcc, v6, v7, v6
	v_fma_f32 v11, -v8, v9, 1.0
	v_fmac_f32_e32 v9, v11, v9
	v_mul_f32_e32 v11, v10, v9
	v_fma_f32 v12, -v8, v11, v10
	v_fmac_f32_e32 v11, v12, v9
	v_fma_f32 v8, -v8, v11, v10
	v_div_fmas_f32 v8, v8, v9, v11
	v_div_fixup_f32 v6, v8, v7, v6
	ds_write_b32 v5, v6 offset:28672
	s_waitcnt vmcnt(0)
	v_mov_b32_e32 v6, v205
	v_mul_f32_e32 v7, 0xbfb8aa3b, v6
	v_exp_f32_e32 v7, v7
	s_nop 0
	v_add_f32_e32 v7, 1.0, v7
	v_div_scale_f32 v8, s[14:15], v7, v7, v6
	v_rcp_f32_e32 v9, v8
	v_div_scale_f32 v10, vcc, v6, v7, v6
	v_fma_f32 v11, -v8, v9, 1.0
	v_fmac_f32_e32 v9, v11, v9
	v_mul_f32_e32 v11, v10, v9
	v_fma_f32 v12, -v8, v11, v10
	v_fmac_f32_e32 v11, v12, v9
	v_fma_f32 v8, -v8, v11, v10
	v_div_fmas_f32 v8, v8, v9, v11
	v_div_fixup_f32 v6, v8, v7, v6
	ds_write_b32 v5, v6 offset:30720
	s_or_b64 exec, exec, s[8:9]
	v_mov_b32_e32 v3, s12
